# 256sq GEMM loops: per-cluster s_setprio flips deleted, one static s_setprio 1 for waves 0-3 per phase
# baseline (speedup 1.0000x reference)
.LBB0_151:
	v_readfirstlane_b32 s98, v228
	s_nop 3
	s_cmp_lt_u32 s98, 0x100
	s_cbranch_scc0 .Lprio_done_158
	s_setprio 1
